# P0a x->bf16/fp8 row loop: 8 row loads hoisted, counted vmcnt
# speedup vs baseline: 1.0022x; 1.0022x over previous
; __device__ __forceinline__ unsigned cvt_pk_bf16(float lo, float hi) { unsigned r; asm("v_cvt_pk_bf16_f32 %0, %1, %2" : "=v"(r) : "v"(lo), "v"(hi)); return r; }
; __device__ __forceinline__ float wave_sum(float s, int) { s += dppf<0x128>(s); s += dppf<0x124>(s); s += dppf<0x122>(s); s += dppf<0x121>(s); return psum32(psum16(s)); }
; __device__ __forceinline__ void p0_prep(const Params& p, unsigned char* lds, int bid, int nb) {
;     ...
;     for (int row = bid * 8 + wid; row < T; row += nb * 8) {
;       const f32x4* src = (const f32x4*)(p.x + (size_t)row * D); float s = 0.f;
; #pragma unroll
;       for (int j = 0; j < 8; ++j) { const f32x4 v = src[lane + 64 * j]; s += v[0] * v[0] + v[1] * v[1] + v[2] * v[2] + v[3] * v[3];
;         u32x2 o; o[0] = cvt_pk_bf16(v[0], v[1]); o[1] = cvt_pk_bf16(v[2], v[3]); *(u32x2*)(xb + (size_t)row * D + (lane + 64 * j) * 4) = o;
;         unsigned q8 = __builtin_amdgcn_cvt_pk_fp8_f32(v[0], v[1], 0, false); q8 = __builtin_amdgcn_cvt_pk_fp8_f32(v[2], v[3], q8, true); *(unsigned*)(xq + (size_t)row * D + (lane + 64 * j) * 4) = q8; }
;       s = wave_sum(s, lane); if (lane == 0) ss0[row] = s;
;     }
.LBB0_5:
	global_load_dwordx4 v[14:17], v[10:11], off offset:-4096
	global_load_dwordx4 v[18:21], v[10:11], off offset:-3072
	global_load_dwordx4 v[24:27], v[10:11], off offset:-2048
	global_load_dwordx4 v[28:31], v[10:11], off offset:-1024
	global_load_dwordx4 v[32:35], v[10:11], off
	global_load_dwordx4 v[36:39], v[10:11], off offset:1024
	global_load_dwordx4 v[40:43], v[10:11], off offset:2048
	global_load_dwordx4 v[44:47], v[10:11], off offset:3072
	s_waitcnt vmcnt(7)
	v_cvt_pk_bf16_f32 v56, v14, v15
	v_cvt_pk_bf16_f32 v57, v16, v17
	v_cvt_pk_fp8_f32 v72, v14, v15
	v_mul_f32_e32 v13, v15, v15
	v_fmac_f32_e32 v13, v14, v14
	v_fmac_f32_e32 v13, v16, v16
	v_cvt_pk_fp8_f32 v72, v16, v17 op_sel:[0,0,1]
	v_fmac_f32_e32 v13, v17, v17
	global_store_dwordx2 v[8:9], v[56:57], off offset:-2048
	global_store_dword v[6:7], v72, off offset:-1024
	s_waitcnt vmcnt(8)
	v_cvt_pk_bf16_f32 v58, v18, v19
	v_cvt_pk_bf16_f32 v59, v20, v21
	v_cvt_pk_fp8_f32 v73, v18, v19
	v_mul_f32_e32 v14, v19, v19
	v_fmac_f32_e32 v14, v18, v18
	v_fmac_f32_e32 v14, v20, v20
	v_cvt_pk_fp8_f32 v73, v20, v21 op_sel:[0,0,1]
	v_fmac_f32_e32 v14, v21, v21
	v_add_f32_e32 v13, v13, v14
	global_store_dwordx2 v[8:9], v[58:59], off offset:-1536
	global_store_dword v[6:7], v73, off offset:-768
	s_waitcnt vmcnt(9)
	v_cvt_pk_bf16_f32 v60, v24, v25
	v_cvt_pk_bf16_f32 v61, v26, v27
	v_cvt_pk_fp8_f32 v74, v24, v25
	v_mul_f32_e32 v14, v25, v25
	v_fmac_f32_e32 v14, v24, v24
	v_fmac_f32_e32 v14, v26, v26
	v_cvt_pk_fp8_f32 v74, v26, v27 op_sel:[0,0,1]
	v_fmac_f32_e32 v14, v27, v27
	v_add_f32_e32 v13, v13, v14
	global_store_dwordx2 v[8:9], v[60:61], off offset:-1024
	global_store_dword v[6:7], v74, off offset:-512
	s_waitcnt vmcnt(10)
	v_cvt_pk_bf16_f32 v62, v28, v29
	v_cvt_pk_bf16_f32 v63, v30, v31
	v_cvt_pk_fp8_f32 v75, v28, v29
	v_mul_f32_e32 v14, v29, v29
	v_fmac_f32_e32 v14, v28, v28
	v_fmac_f32_e32 v14, v30, v30
	v_cvt_pk_fp8_f32 v75, v30, v31 op_sel:[0,0,1]
	v_fmac_f32_e32 v14, v31, v31
	v_add_f32_e32 v13, v13, v14
	global_store_dwordx2 v[8:9], v[62:63], off offset:-512
	global_store_dword v[6:7], v75, off offset:-256
	s_waitcnt vmcnt(11)
	v_cvt_pk_bf16_f32 v64, v32, v33
	v_cvt_pk_bf16_f32 v65, v34, v35
	v_cvt_pk_fp8_f32 v76, v32, v33
	v_mul_f32_e32 v14, v33, v33
	v_fmac_f32_e32 v14, v32, v32
	v_fmac_f32_e32 v14, v34, v34
	v_cvt_pk_fp8_f32 v76, v34, v35 op_sel:[0,0,1]
	v_fmac_f32_e32 v14, v35, v35
	v_add_f32_e32 v13, v13, v14
	global_store_dwordx2 v[8:9], v[64:65], off
	global_store_dword v[6:7], v76, off
	s_waitcnt vmcnt(12)
	v_cvt_pk_bf16_f32 v66, v36, v37
	v_cvt_pk_bf16_f32 v67, v38, v39
	v_cvt_pk_fp8_f32 v77, v36, v37
	v_mul_f32_e32 v14, v37, v37
	v_fmac_f32_e32 v14, v36, v36
	v_fmac_f32_e32 v14, v38, v38
	v_cvt_pk_fp8_f32 v77, v38, v39 op_sel:[0,0,1]
	v_fmac_f32_e32 v14, v39, v39
	v_add_f32_e32 v13, v13, v14
	global_store_dwordx2 v[8:9], v[66:67], off offset:512
	global_store_dword v[6:7], v77, off offset:256
	s_waitcnt vmcnt(13)
	v_cvt_pk_bf16_f32 v68, v40, v41
	v_cvt_pk_bf16_f32 v69, v42, v43
	v_cvt_pk_fp8_f32 v78, v40, v41
	v_mul_f32_e32 v14, v41, v41
	v_fmac_f32_e32 v14, v40, v40
	v_fmac_f32_e32 v14, v42, v42
	v_cvt_pk_fp8_f32 v78, v42, v43 op_sel:[0,0,1]
	v_fmac_f32_e32 v14, v43, v43
	v_add_f32_e32 v13, v13, v14
	global_store_dwordx2 v[8:9], v[68:69], off offset:1024
	global_store_dword v[6:7], v78, off offset:512
	s_waitcnt vmcnt(14)
	v_cvt_pk_bf16_f32 v70, v44, v45
	v_cvt_pk_bf16_f32 v71, v46, v47
	v_cvt_pk_fp8_f32 v79, v44, v45
	v_mul_f32_e32 v16, v45, v45
	v_fmac_f32_e32 v16, v44, v44
	v_fmac_f32_e32 v16, v46, v46
	v_cvt_pk_fp8_f32 v79, v46, v47 op_sel:[0,0,1]
	v_fmac_f32_e32 v16, v47, v47
	v_add_f32_e32 v13, v13, v16
	global_store_dwordx2 v[8:9], v[70:71], off offset:1536
	global_store_dword v[6:7], v79, off offset:768
	v_add_f32_dpp v13, v13, v13 row_ror:8 row_mask:0xf bank_mask:0xf bound_ctrl:1
	s_nop 1
	v_add_f32_dpp v13, v13, v13 row_ror:4 row_mask:0xf bank_mask:0xf bound_ctrl:1
	s_nop 1
	v_add_f32_dpp v13, v13, v13 row_ror:2 row_mask:0xf bank_mask:0xf bound_ctrl:1
	s_nop 1
	v_add_f32_dpp v3, v13, v13 row_ror:1 row_mask:0xf bank_mask:0xf bound_ctrl:1
	v_mov_b32_e32 v13, v3
	s_nop 1
	v_permlane16_swap_b32_e32 v3, v13
	v_add_f32_e32 v3, v3, v13
	v_mov_b32_e32 v13, v3
	s_nop 1
	v_permlane32_swap_b32_e32 v3, v13
	s_and_saveexec_b64 s[4:5], vcc
	s_cbranch_execz .LBB0_4
	v_add_f32_e32 v3, v3, v13
	global_store_dword v[4:5], v3, off
	s_branch .LBB0_4
